# grid barrier: acquire invalidate issued with the arrival atomic instead of after the release
# baseline (speedup 1.0000x reference)
.LBB0_16:
	s_waitcnt vmcnt(0) lgkmcnt(0)
	s_barrier
	s_mov_b64 s[0:1], exec
	v_readlane_b32 s2, v252, 33
	v_readlane_b32 s3, v252, 34
	s_and_b64 s[2:3], s[0:1], s[2:3]
	s_mov_b64 exec, s[2:3]
	s_cbranch_execz .LBB0_22
	buffer_wbl2 sc1
	s_waitcnt vmcnt(0)
	v_readlane_b32 s4, v250, 8
	v_readlane_b32 s5, v250, 9
	v_mov_b32_e32 v0, 1
	s_load_dword s2, s[84:85], 0x0
	s_nop 4
	global_atomic_add v1, v145, v0, s[4:5] sc0
	buffer_inv sc1
	v_readlane_b32 s3, v255, 40
	s_waitcnt lgkmcnt(0)
	s_mul_i32 s2, s2, s12
	s_nop 3
	s_and_b32 s3, s3, 7
	s_lshl_b32 s3, s3, 6
	v_mov_b32_e32 v2, s3
	s_waitcnt vmcnt(0)
	s_nop 0
	v_readfirstlane_b32 s3, v1
	s_nop 3
	s_add_u32 s3, s3, 1
	s_cmp_lg_u32 s3, s2
	s_cbranch_scc1 .Lgb_poll
	global_atomic_add v145, v0, s[4:5] offset:544
	global_atomic_add v145, v0, s[4:5] offset:608
	global_atomic_add v145, v0, s[4:5] offset:672
	global_atomic_add v145, v0, s[4:5] offset:736
	global_atomic_add v145, v0, s[4:5] offset:800
	global_atomic_add v145, v0, s[4:5] offset:864
	global_atomic_add v145, v0, s[4:5] offset:928
	global_atomic_add v145, v0, s[4:5] offset:992
	s_branch .LBB0_22

.Lgb_spin:
	s_sleep 8
	global_load_dword v1, v2, s[4:5] offset:544 sc1
	s_waitcnt vmcnt(0)
	v_cmp_gt_u32_e32 vcc, s12, v1
	s_cbranch_vccnz .Lgb_spin
.LBB0_22:
	s_or_b64 exec, exec, s[0:1]
	s_barrier
